# GQA main loop: the two per-tile taken-branch targets (rescale skips) also aligned to 64 bytes
# baseline (speedup 1.0000x reference)
.LBB0_708:
	s_waitcnt lgkmcnt(0)
	v_mfma_f32_32x32x16_bf16 v[2:17], v[134:137], v[178:181], v[2:17]
	v_exp_f32_e32 v98, v98
	v_exp_f32_e32 v99, v99
	v_exp_f32_e32 v100, v100
	v_exp_f32_e32 v101, v101
	v_mfma_f32_32x32x16_bf16 v[18:33], v[134:137], v[174:177], v[18:33]
	v_exp_f32_e32 v102, v102
	v_exp_f32_e32 v103, v103
	v_exp_f32_e32 v104, v104
	v_exp_f32_e32 v105, v105
	v_add_u32_e32 v78, s21, v206
	ds_read_b128 v[62:65], v78
	ds_read_b128 v[174:177], v78 offset:512
	v_mfma_f32_32x32x16_bf16 v[2:17], v[126:129], v[66:69], v[2:17]
	v_exp_f32_e32 v106, v106
	v_exp_f32_e32 v107, v107
	v_exp_f32_e32 v108, v108
	v_exp_f32_e32 v109, v109
	ds_read_b128 v[178:181], v78 offset:2048
	ds_read_b128 v[170:173], v78 offset:2560
	v_mfma_f32_32x32x16_bf16 v[18:33], v[126:129], v[70:73], v[18:33]
	v_exp_f32_e32 v110, v110
	v_exp_f32_e32 v111, v111
	v_exp_f32_e32 v112, v112
	v_exp_f32_e32 v113, v113
	ds_read_b128 v[166:169], v78 offset:4096
	ds_read_b128 v[162:165], v78 offset:4608
	v_mfma_f32_32x32x16_bf16 v[2:17], v[118:121], v[74:77], v[2:17]
	v_exp_f32_e32 v82, v82
	v_exp_f32_e32 v83, v83
	v_exp_f32_e32 v84, v84
	v_exp_f32_e32 v85, v85
	ds_read_b128 v[158:161], v78 offset:6144
	ds_read_b128 v[154:157], v78 offset:6656
	v_mfma_f32_32x32x16_bf16 v[18:33], v[118:121], v[50:53], v[18:33]
	v_exp_f32_e32 v86, v86
	v_exp_f32_e32 v87, v87
	v_exp_f32_e32 v88, v88
	v_exp_f32_e32 v89, v89
	v_mfma_f32_32x32x16_bf16 v[2:17], v[114:117], v[54:57], v[2:17]
	v_exp_f32_e32 v90, v90
	v_exp_f32_e32 v91, v91
	v_exp_f32_e32 v92, v92
	v_exp_f32_e32 v93, v93
	v_mfma_f32_32x32x16_bf16 v[18:33], v[114:117], v[58:61], v[18:33]
	v_exp_f32_e32 v94, v94
	v_exp_f32_e32 v95, v95
	v_exp_f32_e32 v96, v96
	v_exp_f32_e32 v97, v97
	s_waitcnt vmcnt(2) lgkmcnt(0)
	s_barrier
	s_andn2_b64 vcc, exec, s[4:5]
	s_cbranch_vccnz .LBB0_710
	s_waitcnt lgkmcnt(0)
	v_add_u32_e32 v66, s17, v203
	ds_read_b128 v[50:53], v66 offset:49248
	ds_read_b128 v[54:57], v66 offset:49216
	ds_read_b128 v[58:61], v66 offset:49184
	ds_read_b128 v[66:69], v66 offset:49152
	s_waitcnt lgkmcnt(3)
	v_pk_mul_f32 v[14:15], v[14:15], v[50:51]
	s_waitcnt lgkmcnt(2)
	v_pk_mul_f32 v[10:11], v[10:11], v[54:55]
	s_waitcnt lgkmcnt(1)
	v_pk_mul_f32 v[6:7], v[6:7], v[58:59]
	v_pk_mul_f32 v[16:17], v[16:17], v[52:53]
	v_pk_mul_f32 v[12:13], v[12:13], v[56:57]
	v_pk_mul_f32 v[8:9], v[8:9], v[60:61]
	s_waitcnt lgkmcnt(0)
	v_pk_mul_f32 v[4:5], v[4:5], v[68:69]
	v_pk_mul_f32 v[2:3], v[2:3], v[66:67]
	v_pk_mul_f32 v[30:31], v[30:31], v[50:51]
	v_pk_mul_f32 v[26:27], v[26:27], v[54:55]
	v_pk_mul_f32 v[22:23], v[22:23], v[58:59]
	v_pk_mul_f32 v[32:33], v[32:33], v[52:53]
	v_pk_mul_f32 v[28:29], v[28:29], v[56:57]
	v_pk_mul_f32 v[24:25], v[24:25], v[60:61]
	v_pk_mul_f32 v[20:21], v[20:21], v[68:69]
	v_pk_mul_f32 v[18:19], v[18:19], v[66:67]
	.p2alignl 6, 3212836864

.LBB0_711:
	s_waitcnt lgkmcnt(0)
	v_mfma_f32_32x32x16_bf16 v[2:17], v[134:137], v[150:153], v[2:17]
	v_exp_f32_e32 v66, v66
	v_exp_f32_e32 v67, v67
	v_exp_f32_e32 v68, v68
	v_exp_f32_e32 v69, v69
	v_mfma_f32_32x32x16_bf16 v[18:33], v[134:137], v[146:149], v[18:33]
	v_exp_f32_e32 v70, v70
	v_exp_f32_e32 v71, v71
	v_exp_f32_e32 v72, v72
	v_exp_f32_e32 v73, v73
	v_add_u32_e32 v94, s25, v206
	ds_read_b128 v[174:177], v94
	ds_read_b128 v[170:173], v94 offset:512
	v_mfma_f32_32x32x16_bf16 v[2:17], v[126:129], v[98:101], v[2:17]
	v_exp_f32_e32 v74, v74
	v_exp_f32_e32 v75, v75
	v_exp_f32_e32 v76, v76
	v_exp_f32_e32 v77, v77
	ds_read_b128 v[166:169], v94 offset:2048
	ds_read_b128 v[162:165], v94 offset:2560
	v_mfma_f32_32x32x16_bf16 v[18:33], v[126:129], v[102:105], v[18:33]
	v_exp_f32_e32 v78, v78
	v_exp_f32_e32 v79, v79
	v_exp_f32_e32 v80, v80
	v_exp_f32_e32 v81, v81
	ds_read_b128 v[158:161], v94 offset:4096
	ds_read_b128 v[154:157], v94 offset:4608
	v_mfma_f32_32x32x16_bf16 v[2:17], v[118:121], v[106:109], v[2:17]
	v_exp_f32_e32 v50, v50
	v_exp_f32_e32 v51, v51
	v_exp_f32_e32 v52, v52
	v_exp_f32_e32 v53, v53
	ds_read_b128 v[150:153], v94 offset:6144
	ds_read_b128 v[146:149], v94 offset:6656
	v_mfma_f32_32x32x16_bf16 v[18:33], v[118:121], v[82:85], v[18:33]
	v_exp_f32_e32 v54, v54
	v_exp_f32_e32 v55, v55
	v_exp_f32_e32 v56, v56
	v_exp_f32_e32 v57, v57
	v_mfma_f32_32x32x16_bf16 v[2:17], v[114:117], v[86:89], v[2:17]
	v_exp_f32_e32 v58, v58
	v_exp_f32_e32 v59, v59
	v_exp_f32_e32 v60, v60
	v_exp_f32_e32 v61, v61
	v_mfma_f32_32x32x16_bf16 v[18:33], v[114:117], v[90:93], v[18:33]
	v_exp_f32_e32 v62, v62
	v_exp_f32_e32 v63, v63
	v_exp_f32_e32 v64, v64
	v_exp_f32_e32 v65, v65
	s_waitcnt vmcnt(2) lgkmcnt(0)
	s_barrier
	s_andn2_b64 vcc, exec, s[4:5]
	s_cbranch_vccnz .LBB0_713
	s_waitcnt lgkmcnt(0)
	v_add_u32_e32 v94, s17, v203
	ds_read_b128 v[82:85], v94 offset:49248
	ds_read_b128 v[86:89], v94 offset:49216
	ds_read_b128 v[90:93], v94 offset:49152
	ds_read_b128 v[94:97], v94 offset:49184
	s_waitcnt lgkmcnt(3)
	v_pk_mul_f32 v[16:17], v[16:17], v[84:85]
	v_pk_mul_f32 v[14:15], v[14:15], v[82:83]
	s_waitcnt lgkmcnt(2)
	v_pk_mul_f32 v[12:13], v[12:13], v[88:89]
	v_pk_mul_f32 v[10:11], v[10:11], v[86:87]
	s_waitcnt lgkmcnt(0)
	v_pk_mul_f32 v[8:9], v[8:9], v[96:97]
	v_pk_mul_f32 v[6:7], v[6:7], v[94:95]
	v_pk_mul_f32 v[4:5], v[4:5], v[92:93]
	v_pk_mul_f32 v[2:3], v[2:3], v[90:91]
	v_pk_mul_f32 v[32:33], v[32:33], v[84:85]
	v_pk_mul_f32 v[30:31], v[30:31], v[82:83]
	v_pk_mul_f32 v[28:29], v[28:29], v[88:89]
	v_pk_mul_f32 v[26:27], v[26:27], v[86:87]
	v_pk_mul_f32 v[24:25], v[24:25], v[96:97]
	v_pk_mul_f32 v[22:23], v[22:23], v[94:95]
	v_pk_mul_f32 v[20:21], v[20:21], v[92:93]
	v_pk_mul_f32 v[18:19], v[18:19], v[90:91]
	.p2alignl 6, 3212836864
